# v31 + sec 6.4 MFMA-first segment head: the first half-tile's C-operand init (plain v_fma) is computed before the step barrier; loop flags kept in SGPRs
# speedup vs baseline: 1.0089x; 1.0088x over previous
; #define AT_LOADK(tt) do { const unsigned ko = kgo + (unsigned)(tt) * (64 * BR * 2); ks0 = *(const u32x4*)((const char*)K + ko); ks1 = *(const u32x4*)((const char*)K + ko + 32 * BR * 2); } while (0)
; #define AT_LOADV(tt) do { const unsigned vo = vgo + (unsigned)(tt) * 128; vs0 = *(const u32x4*)((const char*)Vt + vo); vs1 = *(const u32x4*)((const char*)Vt + vo + 64 * SEQ * 2); } while (0)
; __device__ __forceinline__ void attn_unit(int b, int h, int qb, bf16_t* Q, const bf16_t* __restrict__ K, const bf16_t* __restrict__ Vt, const bf16_t* __restrict__ Z, const float* __restrict__ hg, float lam, ...
;     ...
;     const float slope2 = __builtin_bit_cast(float, __builtin_amdgcn_readfirstlane(__builtin_bit_cast(int, tab[h])));
;     bf16x8 qf[2][4];
;     { const bf16_t* qp = Q + (rowbase + qw0 + r32) * BR + h * 128 + 8 * hi;
; #pragma unroll
;       for (int sub = 0; sub < 2; ++sub)
; #pragma unroll
;           for (int d0 = 0; d0 < 4; ++d0) qf[sub][d0] = *(const bf16x8*)(qp + sub * 64 + d0 * 16); }
;     const unsigned kgo = (unsigned)(((rowbase + (tid >> 4)) * BR + h * 128 + (tid & 15) * 8) * 2);
;     const int kl = (tid >> 4) * KROW + (tid & 15) * 16;
;     const unsigned vgo = (unsigned)((((size_t)b * BR + h * 128 + (tid >> 3)) * SEQ + (tid & 7) * 8) * 2);
;     const int vl = AT_VOFF + (tid >> 3) * VROW + (tid & 7) * 16;
;     const int NT = 4 * (qb + 1), last_w = (qw0 + 31) >> 6;
;     int tlo_w = 0; if (Dwin < 4096.f) { const int kmin_w = qw0 - (int)Dwin - 1; tlo_w = kmin_w > 0 ? (kmin_w >> 6) : 0; }
;     f32x16 o[2][4];
; #pragma unroll
;     for (int s = 0; s < 2; ++s)
; #pragma unroll
;         for (int d = 0; d < 4; ++d)
; #pragma unroll
;             for (int r = 0; r < 16; ++r) o[s][d][r] = 0.f;
;     float lsum[2] = {0.f, 0.f};
;     u32x4 ks0, ks1, vs0, vs1;
;     ...
;     AT_LOADK(tfirst); AT_LOADV(tfirst); AT_WRITEK(tfirst & 1); AT_WRITEV(tfirst & 1);
;     __syncthreads();
; __device__ __forceinline__ void attn_phase(const Params& P, LAS unsigned char* lds, int bx, int tid_in) {
;     ...
;         const int h = 15 - (u >> 4), qb = 15 - (u & 15);
;         const float Df = tab[16 + h];
;         int tfirst = 0;
;         if (Df < 4096.f) { const int kmin = qb * 256 - (int)Df - 1; tfirst = kmin > 0 ? (kmin >> 6) : 0; }
;         tfirst = __builtin_amdgcn_readfirstlane(tfirst);
.LBB0_243:
	s_or_b64 exec, exec, s[8:9]
	s_ashr_i32 s10, s11, 4
	s_sub_i32 s18, 31, s10
	s_sub_i32 s8, 15, s10
	s_andn2_b32 s11, 15, s11
	s_lshl_b32 s62, s18, 2
	s_add_i32 s62, s62, 0x112c0
	v_mov_b32_e32 v0, s62
	ds_read_b32 v0, v0
	s_lshl_b32 s62, s11, 8
	s_mov_b32 s9, s19
	v_mov_b32_e32 v223, v211
	v_mov_b32_e32 v225, 0
	v_mov_b32_e32 v224, v225
	v_mov_b32_e32 v79, v225
	v_mov_b32_e32 v78, v225
	v_mov_b32_e32 v77, v225
	v_mov_b32_e32 v76, v225
	v_mov_b32_e32 v75, v225
	v_mov_b32_e32 v74, v225
	v_mov_b32_e32 v73, v225
	v_mov_b32_e32 v72, v225
	v_mov_b32_e32 v71, v225
	v_mov_b32_e32 v70, v225
	v_mov_b32_e32 v69, v225
	v_mov_b32_e32 v68, v225
	v_mov_b32_e32 v67, v225
	v_mov_b32_e32 v66, v225
	v_mov_b32_e32 v65, v225
	v_mov_b32_e32 v64, v225
	v_mov_b32_e32 v63, v225
	v_mov_b32_e32 v62, v225
	v_mov_b32_e32 v61, v225
	v_mov_b32_e32 v60, v225
	v_mov_b32_e32 v59, v225
	v_mov_b32_e32 v58, v225
	v_mov_b32_e32 v57, v225
	v_mov_b32_e32 v56, v225
	v_mov_b32_e32 v55, v225
	v_mov_b32_e32 v54, v225
	v_mov_b32_e32 v53, v225
	v_mov_b32_e32 v52, v225
	v_mov_b32_e32 v51, v225
	v_mov_b32_e32 v50, v225
	v_mov_b32_e32 v49, v225
	v_mov_b32_e32 v48, v225
	v_mov_b32_e32 v31, v225
	v_mov_b32_e32 v30, v225
	v_mov_b32_e32 v29, v225
	v_mov_b32_e32 v28, v225
	v_mov_b32_e32 v27, v225
	v_mov_b32_e32 v26, v225
	v_mov_b32_e32 v25, v225
	v_mov_b32_e32 v24, v225
	v_mov_b32_e32 v23, v225
	v_mov_b32_e32 v22, v225
	v_mov_b32_e32 v21, v225
	v_mov_b32_e32 v20, v225
	v_mov_b32_e32 v19, v225
	v_mov_b32_e32 v18, v225
	v_mov_b32_e32 v17, v225
	v_mov_b32_e32 v16, v225
	v_mov_b32_e32 v15, v225
	v_mov_b32_e32 v14, v225
	v_mov_b32_e32 v13, v225
	v_mov_b32_e32 v12, v225
	v_mov_b32_e32 v11, v225
	v_mov_b32_e32 v10, v225
	v_mov_b32_e32 v9, v225
	v_mov_b32_e32 v8, v225
	v_mov_b32_e32 v7, v225
	v_mov_b32_e32 v6, v225
	v_mov_b32_e32 v5, v225
	v_mov_b32_e32 v4, v225
	v_mov_b32_e32 v127, v225
	v_mov_b32_e32 v126, v225
	v_mov_b32_e32 v125, v225
	v_mov_b32_e32 v124, v225
	v_mov_b32_e32 v123, v225
	v_mov_b32_e32 v122, v225
	v_mov_b32_e32 v121, v225
	v_mov_b32_e32 v120, v225
	v_mov_b32_e32 v119, v225
	v_mov_b32_e32 v118, v225
	v_mov_b32_e32 v117, v225
	v_mov_b32_e32 v116, v225
	v_mov_b32_e32 v115, v225
	v_mov_b32_e32 v114, v225
	s_waitcnt lgkmcnt(0)
	v_cvt_i32_f32_e32 v1, v0
	v_cmp_gt_f32_e32 vcc, s78, v0
	v_mov_b32_e32 v113, v225
	v_mov_b32_e32 v112, v225
	v_readfirstlane_b32 s18, v1
	s_not_b32 s63, s18
	s_add_i32 s18, s62, s63
	s_max_i32 s18, s18, 0
	s_lshr_b32 s18, s18, 6
	s_and_b64 s[64:65], vcc, exec
	s_cselect_b32 s64, s18, 0
	s_add_i32 s84, s62, s75
	s_lshl_b64 s[66:67], s[8:9], 2
	s_add_u32 s86, s73, s66
	s_addc_u32 s87, s74, s67
	s_ashr_i32 s9, s84, 31
	s_add_u32 s82, s84, s76
	s_addc_u32 s83, s9, 0
	s_lshl_b32 s18, s8, 7
	s_lshl_b32 s8, s8, 8
	s_lshl_b32 s65, s64, 18
	s_add_i32 s8, s65, s8
	v_add_u32_e32 v0, s18, v231
	v_add_u32_e32 v210, s8, v232
	s_lshl_b32 s66, s64, 7
	v_lshl_or_b32 v2, v0, 13, v218
	v_lshl_add_u64 v[0:1], s[38:39], 0, v[210:211]
	v_or_b32_e32 v32, s82, v214
	v_mov_b32_e32 v33, s83
	global_load_dwordx4 v[160:163], v210, s[38:39]
	v_add_u32_e32 v210, s66, v2
	v_add_co_u32_e64 v0, s[8:9], s79, v0
	v_lshlrev_b64 v[32:33], 12, v[32:33]
	s_nop 0
	v_addc_co_u32_e64 v1, s[8:9], 0, v1, s[8:9]
	v_lshl_add_u64 v[2:3], s[36:37], 0, v[210:211]
	v_lshl_add_u64 v[32:33], s[34:35], 0, v[32:33]
	global_load_dword v34, v211, s[86:87]
	global_load_dwordx4 v[164:167], v210, s[36:37]
	global_load_dwordx4 v[168:171], v[0:1], off
	v_add_co_u32_e64 v0, s[8:9], s80, v2
	v_lshl_add_u64 v[32:33], s[18:19], 1, v[32:33]
	s_nop 0
	v_addc_co_u32_e64 v1, s[8:9], 0, v3, s[8:9]
	v_lshl_add_u64 v[32:33], v[32:33], 0, v[222:223]
	global_load_dwordx4 v[172:175], v[0:1], off
	global_load_dwordx4 v[176:179], v[32:33], off
	global_load_dwordx4 v[180:183], v[32:33], off offset:32
	global_load_dwordx4 v[184:187], v[32:33], off offset:64
	global_load_dwordx4 v[188:191], v[32:33], off offset:96
	global_load_dwordx4 v[192:195], v[32:33], off offset:128
	global_load_dwordx4 v[196:199], v[32:33], off offset:160
	global_load_dwordx4 v[200:203], v[32:33], off offset:192
	global_load_dwordx4 v[204:207], v[32:33], off offset:224
	s_lshl_b32 s85, s11, 2
	s_add_i32 s85, s85, 4
	s_bitcmp1_b32 s64, 0
	s_cselect_b32 s8, 0x4400, 0
	s_add_i32 s8, s8, 0
	v_add_u32_e32 v33, s8, v220
	v_add_u32_e32 v32, s8, v216
	v_add_u32_e32 v35, 0x8800, v33
	v_add_u32_e32 v33, 0xaa00, v33
	v_mov_b32_e32 v3, v225
	v_mov_b32_e32 v2, v225
	v_mov_b32_e32 v1, v225
	v_mov_b32_e32 v0, v225
	v_mov_b32_e32 v111, v225
	v_mov_b32_e32 v110, v225
	v_mov_b32_e32 v109, v225
	v_mov_b32_e32 v108, v225
	v_mov_b32_e32 v107, v225
	v_mov_b32_e32 v106, v225
	v_mov_b32_e32 v105, v225
	v_mov_b32_e32 v104, v225
	v_mov_b32_e32 v103, v225
	v_mov_b32_e32 v102, v225
	v_mov_b32_e32 v101, v225
	v_mov_b32_e32 v100, v225
	v_mov_b32_e32 v99, v225
	v_mov_b32_e32 v98, v225
	v_mov_b32_e32 v97, v225
	v_mov_b32_e32 v96, v225
	v_mov_b32_e32 v95, v225
	v_mov_b32_e32 v94, v225
	v_mov_b32_e32 v93, v225
	v_mov_b32_e32 v92, v225
	v_mov_b32_e32 v91, v225
	s_cmp_ge_i32 s64, s85
	v_mov_b32_e32 v90, v225
	v_mov_b32_e32 v89, v225
	v_mov_b32_e32 v88, v225
	v_mov_b32_e32 v87, v225
	v_mov_b32_e32 v86, v225
	v_mov_b32_e32 v85, v225
	v_mov_b32_e32 v84, v225
	v_mov_b32_e32 v83, v225
	v_mov_b32_e32 v82, v225
	v_mov_b32_e32 v81, v225
	v_mov_b32_e32 v80, v225
	v_mov_b32_e32 v47, v225
	v_mov_b32_e32 v46, v225
	v_mov_b32_e32 v45, v225
	v_mov_b32_e32 v44, v225
	s_waitcnt vmcnt(12)
	ds_write_b128 v32, v[160:163]
	s_waitcnt vmcnt(9)
	ds_write_b128 v32, v[168:171] offset:8704
	ds_write2_b64 v35, v[164:165], v[166:167] offset1:1
	s_waitcnt vmcnt(8)
	ds_write2_b64 v33, v[172:173], v[174:175] offset1:1
	v_readfirstlane_b32 s86, v34
	v_mov_b32_e32 v43, v225
	v_mov_b32_e32 v42, v225
	v_mov_b32_e32 v41, v225
	v_mov_b32_e32 v40, v225
	v_mov_b32_e32 v39, v225
	v_mov_b32_e32 v38, v225
	v_mov_b32_e32 v37, v225
	v_mov_b32_e32 v36, v225
	v_mov_b32_e32 v35, v225
	v_mov_b32_e32 v34, v225
	v_mov_b32_e32 v33, v225
	v_mov_b32_e32 v32, v225
	s_waitcnt lgkmcnt(0)
	s_barrier
; #define LAS __attribute__((address_space(3)))
; #define AT_LOADK(tt) do { const unsigned ko = kgo + (unsigned)(tt) * (64 * BR * 2); ks0 = *(const u32x4*)((const char*)K + ko); ks1 = *(const u32x4*)((const char*)K + ko + 32 * BR * 2); } while (0)
; template <int HF> ...
;     ...
;     float s2v = slope2; asm volatile("" : "+v"(s2v));
;     const float tb = slope2 * (float)(kvh0 + 4 * hi - qw0 - r32) - SB;
; #pragma unroll
;     for (int sub = 0; sub < 2; ++sub) {
;         f32x16 p;
; #pragma unroll
;         for (int r = 0; r < 16; ++r) p[r] = __builtin_fmaf(s2v, (float)((r & 3) + 8 * (r >> 2)), tb);
; __device__ __forceinline__ void attn_unit(int b, int h, int qb, bf16_t* Q, const bf16_t* __restrict__ K, const bf16_t* __restrict__ Vt, const bf16_t* __restrict__ Z, const float* __restrict__ hg, float lam, ...
;     ...
;     for (int t = tfirst; t < NT; ++t) {
;         const int cur = t & 1; const bool more = (t + 1 < NT), active = (t <= last_w) && (t >= tlo_w), band = (64 * t + 63 > qw0);
;         const LAS unsigned char* kb = lds + cur * KT_BYTES + r32 * KROW + hi * 16;
;         const LAS unsigned char* vb = lds + AT_VOFF + cur * VT_BYTES + r32 * VROW + hi * 8;
;         if (more) AT_LOADK(t + 1);
	s_cbranch_scc1 .LBB0_236
	s_add_i32 s8, s84, s63
	s_max_i32 s8, s8, 0
	s_ashr_i32 s87, s84, 6
	s_lshr_b32 s11, s8, 6
	s_and_b64 s[8:9], vcc, exec
	s_cselect_b32 s88, s11, 0
	v_add_u32_e32 v0, s62, v239
	s_lshl_b32 s89, s64, 6
	v_subrev_u32_e32 v223, s89, v0
	v_add_u32_e32 v0, s62, v238
	v_sub_u32_e32 v246, v237, v0
	v_add_u32_e32 v0, s66, v240
	s_lshl_b32 s8, s10, 20
	v_subrev_u32_e32 v226, s8, v0
	v_add_u32_e32 v0, s65, v241
	s_lshl_b32 s8, s10, 8
	v_mov_b32_e32 v32, v211
	v_mov_b32_e32 v33, v211
	v_mov_b32_e32 v46, v211
	v_mov_b32_e32 v47, v211
	v_subrev_u32_e32 v210, s8, v0
	v_mov_b32_e32 v34, v211
	v_mov_b32_e32 v35, v211
	v_mov_b32_e32 v36, v211
	v_mov_b32_e32 v37, v211
	v_mov_b32_e32 v38, v211
	v_mov_b32_e32 v39, v211
	v_mov_b32_e32 v40, v211
	v_mov_b32_e32 v41, v211
	v_mov_b32_e32 v42, v211
	v_mov_b32_e32 v43, v211
	v_mov_b32_e32 v44, v211
	v_mov_b32_e32 v45, v211
	v_mov_b32_e32 v224, 0
	v_mov_b64_e32 v[94:95], v[46:47]
	v_mov_b64_e32 v[110:111], v[46:47]
	v_mov_b64_e32 v[126:127], v[46:47]
	v_mov_b64_e32 v[0:1], v[32:33]
	v_mov_b64_e32 v[16:17], v[32:33]
	v_mov_b64_e32 v[62:63], v[46:47]
	v_mov_b64_e32 v[78:79], v[46:47]
	v_mov_b64_e32 v[92:93], v[44:45]
	v_mov_b64_e32 v[90:91], v[42:43]
	v_mov_b64_e32 v[88:89], v[40:41]
	v_mov_b64_e32 v[86:87], v[38:39]
	v_mov_b64_e32 v[84:85], v[36:37]
	v_mov_b64_e32 v[82:83], v[34:35]
	v_mov_b64_e32 v[80:81], v[32:33]
	v_mov_b64_e32 v[108:109], v[44:45]
	v_mov_b64_e32 v[106:107], v[42:43]
	v_mov_b64_e32 v[104:105], v[40:41]
	v_mov_b64_e32 v[102:103], v[38:39]
	v_mov_b64_e32 v[100:101], v[36:37]
	v_mov_b64_e32 v[98:99], v[34:35]
	v_mov_b64_e32 v[96:97], v[32:33]
	v_mov_b64_e32 v[124:125], v[44:45]
	v_mov_b64_e32 v[122:123], v[42:43]
	v_mov_b64_e32 v[120:121], v[40:41]
	v_mov_b64_e32 v[118:119], v[38:39]
	v_mov_b64_e32 v[116:117], v[36:37]
	v_mov_b64_e32 v[114:115], v[34:35]
	v_mov_b64_e32 v[112:113], v[32:33]
	v_mov_b64_e32 v[2:3], v[34:35]
	v_mov_b64_e32 v[4:5], v[36:37]
	v_mov_b64_e32 v[6:7], v[38:39]
	v_mov_b64_e32 v[8:9], v[40:41]
	v_mov_b64_e32 v[10:11], v[42:43]
	v_mov_b64_e32 v[12:13], v[44:45]
	v_mov_b64_e32 v[14:15], v[46:47]
	v_mov_b64_e32 v[18:19], v[34:35]
	v_mov_b64_e32 v[20:21], v[36:37]
	v_mov_b64_e32 v[22:23], v[38:39]
	v_mov_b64_e32 v[24:25], v[40:41]
	v_mov_b64_e32 v[26:27], v[42:43]
	v_mov_b64_e32 v[28:29], v[44:45]
	v_mov_b64_e32 v[30:31], v[46:47]
	v_mov_b64_e32 v[60:61], v[44:45]
	v_mov_b64_e32 v[58:59], v[42:43]
	v_mov_b64_e32 v[56:57], v[40:41]
	v_mov_b64_e32 v[54:55], v[38:39]
	v_mov_b64_e32 v[52:53], v[36:37]
	v_mov_b64_e32 v[50:51], v[34:35]
	v_mov_b64_e32 v[48:49], v[32:33]
	v_mov_b64_e32 v[76:77], v[44:45]
	v_mov_b64_e32 v[74:75], v[42:43]
	v_mov_b64_e32 v[72:73], v[40:41]
	v_mov_b64_e32 v[70:71], v[38:39]
	v_mov_b64_e32 v[68:69], v[36:37]
	v_mov_b64_e32 v[66:67], v[34:35]
	v_mov_b64_e32 v[64:65], v[32:33]
	v_mov_b32_e32 v225, v224
	global_load_dwordx4 v[160:163], v210, s[38:39]
	v_add_u32_e32 v128, 0x20000, v210
	global_load_dwordx4 v[168:171], v128, s[38:39]
	global_load_dwordx4 v[164:167], v226, s[36:37]
	v_add_u32_e32 v128, 0x80000, v226
	global_load_dwordx4 v[172:175], v128, s[36:37]
	v_mov_b32_e32 v142, s86
	v_add_u32_e32 v128, s89, v246
	v_cvt_f32_i32_e32 v128, v128
	v_mov_b32_e32 v129, s72
	v_add_u32_e32 v227, 32, v223
	v_fma_f32 v144, s86, v128, -v129
	v_fma_f32 v128, 0, v142, v144
	v_add_f32_e32 v129, v144, v142
	v_fma_f32 v131, v142, s21, v144
	v_fma_f32 v130, v142, s20, v144
	v_fma_f32 v133, v142, s23, v144
	v_fma_f32 v132, v142, s22, v144
	v_fma_f32 v135, v142, s41, v144
	v_fma_f32 v134, v142, s40, v144
	v_fma_f32 v137, v142, s43, v144
	v_fma_f32 v136, v142, s42, v144
	v_fma_f32 v139, v142, s53, v144
	v_fma_f32 v138, v142, s52, v144
	v_fma_f32 v141, v142, s59, v144
	v_fma_f32 v140, v142, s58, v144
	v_fma_f32 v143, v142, s61, v144
	v_fma_f32 v142, v142, s60, v144
	.p2align 6

; #define LAS __attribute__((address_space(3)))
; template <int HF> ...
;     ...
;         for (int r = 0; r < 16; ++r) p[r] = __builtin_fmaf(s2v, (float)((r & 3) + 8 * (r >> 2)), tb);
; #pragma unroll
;         for (int d0 = 0; d0 < 4; ++d0) { const bf16x8 kf = *(const LAS bf16x8*)(kb + HF * 32 * KROW + sub * 128 + d0 * 32);
;             p = __builtin_amdgcn_mfma_f32_32x32x16_bf16(kf, qf[sub][d0], p, 0, 0, 0); }
;         if (band) { const int lim = qw0 + r32 - (kvh0 + 4 * hi);
;             asm volatile("s_nop 15" : "+v"(p));
;             const float ninf = -INFINITY;
; #pragma unroll
;             for (int r = 0; r < 16; ++r) asm("v_cmp_gt_i32_e32 vcc, %2, %1\n\tv_cndmask_b32_e32 %0, %0, %3, vcc" : "+v"(p[r]) : "v"(lim), "i"((r & 3) + 8 * (r >> 2)), "v"(ninf) : "vcc"); }
.LBB0_251:
	s_mul_i32 s91, s92, 0x4400
	s_andn2_b64 vcc, exec, s[66:67]
	v_add_u32_e32 v247, s91, v235
	s_cbranch_vccnz .LBB0_259
	ds_read_b128 v[248:251], v247
	ds_read_b128 v[252:255], v247 offset:32
	s_and_b64 vcc, exec, s[10:11]
	s_waitcnt vmcnt(7) lgkmcnt(1)
	s_nop 0
	v_mfma_f32_32x32x16_bf16 v[144:159], v[248:251], v[176:179], v[128:143]
	s_waitcnt vmcnt(6) lgkmcnt(0)
	v_mfma_f32_32x32x16_bf16 v[144:159], v[252:255], v[180:183], v[144:159]
	ds_read_b128 v[248:251], v247 offset:64
	ds_read_b128 v[252:255], v247 offset:96
	s_waitcnt vmcnt(5) lgkmcnt(1)
	v_mfma_f32_32x32x16_bf16 v[144:159], v[248:251], v[184:187], v[144:159]
	s_waitcnt vmcnt(4) lgkmcnt(0)
	v_mfma_f32_32x32x16_bf16 v[144:159], v[252:255], v[188:191], v[144:159]
	s_cbranch_vccnz .LBB0_254
	s_nop 15
	s_nop 0
	v_cmp_gt_i32_e32 vcc, 0, v227
	v_cndmask_b32_e32 v144, v144, v244, vcc
	s_nop 0
	v_cmp_gt_i32_e32 vcc, 1, v227
	v_cndmask_b32_e32 v145, v145, v244, vcc
	s_nop 0
	v_cmp_gt_i32_e32 vcc, 2, v227
	v_cndmask_b32_e32 v146, v146, v244, vcc
	s_nop 0
	v_cmp_gt_i32_e32 vcc, 3, v227
	v_cndmask_b32_e32 v147, v147, v244, vcc
	s_nop 0
	v_cmp_gt_i32_e32 vcc, 8, v227
	v_cndmask_b32_e32 v148, v148, v244, vcc
	s_nop 0
	v_cmp_gt_i32_e32 vcc, 9, v227
	v_cndmask_b32_e32 v149, v149, v244, vcc
	s_nop 0
	v_cmp_gt_i32_e32 vcc, 10, v227
	v_cndmask_b32_e32 v150, v150, v244, vcc
	s_nop 0
	v_cmp_gt_i32_e32 vcc, 11, v227
	v_cndmask_b32_e32 v151, v151, v244, vcc
	s_nop 0
	v_cmp_gt_i32_e32 vcc, 16, v227
	v_cndmask_b32_e32 v152, v152, v244, vcc
	s_nop 0
	v_cmp_gt_i32_e32 vcc, 17, v227
	v_cndmask_b32_e32 v153, v153, v244, vcc
	s_nop 0
	v_cmp_gt_i32_e32 vcc, 18, v227
	v_cndmask_b32_e32 v154, v154, v244, vcc
	s_nop 0
	v_cmp_gt_i32_e32 vcc, 19, v227
	v_cndmask_b32_e32 v155, v155, v244, vcc
	s_nop 0
	v_cmp_gt_i32_e32 vcc, 24, v227
	v_cndmask_b32_e32 v156, v156, v244, vcc
	s_nop 0
	v_cmp_gt_i32_e32 vcc, 25, v227
	v_cndmask_b32_e32 v157, v157, v244, vcc
	s_nop 0
	v_cmp_gt_i32_e32 vcc, 26, v227
	v_cndmask_b32_e32 v158, v158, v244, vcc
	s_nop 0
	v_cmp_gt_i32_e32 vcc, 27, v227
	v_cndmask_b32_e32 v159, v159, v244, vcc

; template <int HF> ...
;     ...
;     float s2v = slope2; asm volatile("" : "+v"(s2v));
;     const float tb = slope2 * (float)(kvh0 + 4 * hi - qw0 - r32) - SB;
; #pragma unroll
;     for (int sub = 0; sub < 2; ++sub) {
;         f32x16 p;
; #pragma unroll
;         for (int r = 0; r < 16; ++r) p[r] = __builtin_fmaf(s2v, (float)((r & 3) + 8 * (r >> 2)), tb);
.LBB0_273:
	v_subrev_u32_e32 v223, 64, v223
	s_add_i32 s89, s89, 64
	v_add_u32_e32 v226, 0x80, v226
	s_andn2_b64 vcc, exec, s[62:63]
	v_add_u32_e32 v210, 0x40000, v210
	s_nop 3
	v_mov_b32_e32 v142, s86
	v_add_u32_e32 v128, s89, v246
	v_cvt_f32_i32_e32 v128, v128
	v_mov_b32_e32 v129, s72
	v_add_u32_e32 v227, 32, v223
	v_fma_f32 v144, s86, v128, -v129
	v_fma_f32 v128, 0, v142, v144
	v_add_f32_e32 v129, v144, v142
	v_fma_f32 v131, v142, s21, v144
	v_fma_f32 v130, v142, s20, v144
	v_fma_f32 v133, v142, s23, v144
	v_fma_f32 v132, v142, s22, v144
	v_fma_f32 v135, v142, s41, v144
	v_fma_f32 v134, v142, s40, v144
	v_fma_f32 v137, v142, s43, v144
	v_fma_f32 v136, v142, s42, v144
	v_fma_f32 v139, v142, s53, v144
	v_fma_f32 v138, v142, s52, v144
	v_fma_f32 v141, v142, s59, v144
	v_fma_f32 v140, v142, s58, v144
	v_fma_f32 v143, v142, s61, v144
	v_fma_f32 v142, v142, s60, v144
	s_waitcnt lgkmcnt(0)
	s_barrier
	s_cbranch_vccz .LBB0_236
	s_mov_b32 s64, s90
	s_branch .LBB0_245
